# diff tile loop unrolled x2 by LDS-buffer parity: K/V staging writes and fragment reads use loop-invariant bases + immediate offsets (8 fewer VALU per tile)
# speedup vs baseline: 1.0211x; 1.0081x over previous
; #define ALAS __attribute__((address_space(3)))
; __device__ __forceinline__ void diff_unit(int b, int hd, int qb, const bf16_t* Q, const bf16_t* K, const bf16_t* VT, bf16_t* O, const float* biasd, float lam, const float* subg, ALAS unsigned char* lds) {
;     ...
;     const int NT = 2 * (qb + 1);
;     const bf16_t* kg[2]; const bf16_t* vg[2]; int kl[2], vl[2];
; #pragma unroll
;     for (int i = 0; i < 2; ++i) { const int c = tid + 512 * i; const int key = c >> 4, part = c & 15;
;         kg[i] = K + (tok0 + key) * 1024 + hd * 128 + part * 8; kl[i] = ((part >> 3) * 64 + key) * ROWB + (part & 7) * 16;
;         const int d = c >> 3, pv = c & 7; vg[i] = VT + (size_t)(hd * 128 + d) * MTOK + tok0 + pv * 8; vl[i] = 18432 + d * ROWB + pv * 16; }
;     u32x4 kr[2], vr[2];
; #pragma unroll
;     for (int i = 0; i < 2; ++i) { kr[i] = *(const u32x4*)(kg[i]); vr[i] = *(const u32x4*)(vg[i]); }
;     f32x16 o[4]; float mref = 0.f, lsum = 0.f;
; #pragma unroll
;     for (int d = 0; d < 4; ++d)
; #pragma unroll
;         for (int r = 0; r < 16; ++r) o[d][r] = 0.f;
;     for (int t = 0; t < NT; ++t) {
;         ALAS unsigned char* buf = lds + (t & 1) * 36864;
; #pragma unroll
;         for (int i = 0; i < 2; ++i) { *(ALAS u32x4*)(buf + kl[i]) = kr[i]; *(ALAS u32x4*)(buf + vl[i]) = vr[i]; }
;         __syncthreads();
;         if (t + 1 < NT) {
; #pragma unroll
;             for (int i = 0; i < 2; ++i) { kr[i] = *(const u32x4*)(kg[i] + (size_t)(t + 1) * 64 * 1024); vr[i] = *(const u32x4*)(vg[i] + (t + 1) * 64); }
;         }
;         const int kbase = 64 * t;
;         if (kbase <= q0 + 31) {
.LBB0_502:
	s_lshr_b32 s17, s1, 2
	s_lshl_b32 s4, s0, 11
	s_and_b32 s4, s4, 0x3800000
	s_and_b32 s17, s17, 7
	v_lshlrev_b64 v[64:65], 11, v[64:65]
	s_lshl_b32 s17, s17, 8
	v_lshl_add_u64 v[64:65], s[4:5], 0, v[64:65]
	v_readlane_b32 s36, v255, 20
	v_or3_b32 v64, v64, s17, v144
	v_readlane_b32 s37, v255, 21
	s_lshl_b32 s18, s14, 1
	s_add_i32 s12, s12, s13
	v_lshl_add_u64 v[164:165], s[36:37], 0, v[64:65]
	v_lshlrev_b64 v[64:65], 11, v[66:67]
	v_lshl_add_u64 v[64:65], s[4:5], 0, v[64:65]
	v_or3_b32 v64, v64, s17, v144
	s_or_b32 s15, s15, 31
	s_mov_b32 s14, 2
	s_add_i32 s16, s18, 2
	v_mov_b32_e32 v131, v136
	s_addk_i32 s12, 0xff81
	v_sub_u32_e32 v159, v70, v134
	v_lshl_add_u64 v[166:167], s[36:37], 0, v[64:65]
	s_not_b32 s13, s18
	s_mov_b32 s17, 64
	v_add3_u32 v146, s11, v139, v130
	v_add3_u32 v147, v143, v130, s35
	s_branch .LBB0_504

; #define ALAS __attribute__((address_space(3)))
; __device__ __forceinline__ int kperm(int i) { return (i & 19) | ((i & 4) << 1) | ((i & 8) >> 1); }
; template <int OFF> __device__ __forceinline__ void ldsr(bf16x8& d, unsigned a) { asm volatile("ds_read_b128 %0, %1 offset:%c2" : "=v"(d) : "v"(a), "i"(OFF) : "memory"); }
; __device__ __forceinline__ void qk_tile(f32x16& s0, f32x16& s1, float ci, const ALAS unsigned char* Kb, const bf16x8 (&qf)[4], int r32, int hi) {
;     const unsigned p0 = (unsigned)(uintptr_t)(Kb + kperm(r32) * ROWB + hi * 16);
;     bf16x8 a[8];
;     ldsr<0>(a[0], p0); ldsr<32 * ROWB>(a[1], p0); ldsr<32>(a[2], p0); ldsr<32 * ROWB + 32>(a[3], p0);
;     ldsr<64>(a[4], p0); ldsr<32 * ROWB + 64>(a[5], p0); ldsr<96>(a[6], p0); ldsr<32 * ROWB + 96>(a[7], p0);
; __device__ __forceinline__ void diff_unit(int b, int hd, int qb, const bf16_t* Q, const bf16_t* K, const bf16_t* VT, bf16_t* O, const float* biasd, float lam, const float* subg, ALAS unsigned char* lds) {
;     ...
;         ALAS unsigned char* buf = lds + (t & 1) * 36864;
; #pragma unroll
;         for (int i = 0; i < 2; ++i) { *(ALAS u32x4*)(buf + kl[i]) = kr[i]; *(ALAS u32x4*)(buf + vl[i]) = vr[i]; }
;         __syncthreads();
;         if (t + 1 < NT) {
; #pragma unroll
;             for (int i = 0; i < 2; ++i) { kr[i] = *(const u32x4*)(kg[i] + (size_t)(t + 1) * 64 * 1024); vr[i] = *(const u32x4*)(vg[i] + (t + 1) * 64); }
;         }
.Ldf_504b:
	s_bitcmp1_b32 s14, 0
	s_cselect_b32 s4, 0, 0x9000
	s_add_i32 s18, s4, 0
	s_waitcnt vmcnt(3)
	ds_write_b128 v138, v[112:115] offset:0
	s_waitcnt vmcnt(1)
	ds_write_b128 v158, v[116:119] offset:18432
	ds_write_b128 v142, v[120:123] offset:0
	s_cmp_ge_i32 s14, s16
	s_waitcnt vmcnt(0)
	ds_write_b128 v160, v[124:127] offset:18432
	s_waitcnt lgkmcnt(0)
	s_barrier
	ds_read_b128 v[172:175], v146 offset:0
	ds_read_b128 v[176:179], v146 offset:4608
	ds_read_b128 v[180:183], v146 offset:32
	ds_read_b128 v[184:187], v146 offset:4640
	ds_read_b128 v[188:191], v146 offset:64
	ds_read_b128 v[192:195], v146 offset:4672
	ds_read_b128 v[196:199], v146 offset:96
	ds_read_b128 v[216:219], v146 offset:4704
	s_cbranch_scc1 .Ldf_506b
	s_add_i32 s4, s17, 64
	s_lshl_b64 s[36:37], s[4:5], 1
	v_lshl_add_u64 v[64:65], v[156:157], 0, s[36:37]
	v_lshl_add_u64 v[66:67], v[140:141], 0, s[36:37]
	global_load_dwordx4 v[112:115], v[164:165], off
	global_load_dwordx4 v[120:123], v[166:167], off
	global_load_dwordx4 v[116:119], v[66:67], off
	global_load_dwordx4 v[124:127], v[64:65], off

; #define ALAS __attribute__((address_space(3)))
; __device__ __forceinline__ float ex2(float x) { return __builtin_amdgcn_exp2f(x); }
; template <int NDB> __device__ __forceinline__ void wait_v(bf16x8 (&v)[2 * NDB]) { if constexpr (NDB == 4) lds_wait8(v); else lds_wait4(v); }
; template <int NDB>
; __device__ __forceinline__ void softmax_pv(f32x16& s0, f32x16& s1, float& mref, float& lsum, f32x16 (&o)[NDB], const ALAS unsigned char* Vb, int r32, int hi) {
;     const unsigned vp = (unsigned)(uintptr_t)(Vb + r32 * ROWB + hi * 16);
;     bf16x8 va[2 * NDB], vb[2 * NDB];
;     issue_v<NDB, 0>(va, vp);
;     float ps = 0.f;
; #pragma unroll
;     for (int r = 0; r < 16; ++r) { s0[r] = ex2(s0[r]); ps += s0[r]; }
;     bf16x8 pf0, pf1, pf2, pf3;
;     pack16(s0, pf0, pf1);
;     wait_v<NDB>(va);
;     issue_v<NDB, 1>(vb, vp);
;     __builtin_amdgcn_sched_barrier(0);
; #pragma unroll
;     for (int d = 0; d < NDB; ++d) o[d] = __builtin_amdgcn_mfma_f32_32x32x16_bf16(va[d], pf0, o[d], 0, 0, 0);
; #pragma unroll
;     for (int d = 0; d < NDB; ++d) o[d] = __builtin_amdgcn_mfma_f32_32x32x16_bf16(va[NDB + d], pf1, o[d], 0, 0, 0);
; #pragma unroll
;     for (int r = 0; r < 16; ++r) { s1[r] = ex2(s1[r]); ps += s1[r]; }
;     pack16(s1, pf2, pf3);
; #pragma unroll
;     for (int i = 0; i < 2 * NDB; ++i) { __builtin_amdgcn_sched_group_barrier(0x008, 1, 0); __builtin_amdgcn_sched_group_barrier(0x002, (NDB == 4 ? 5 : 10), 0); }
;     __builtin_amdgcn_sched_barrier(0);
;     wait_v<NDB>(vb);
;     __builtin_amdgcn_sched_barrier(0);
; #pragma unroll
;     for (int d = 0; d < NDB; ++d) o[d] = __builtin_amdgcn_mfma_f32_32x32x16_bf16(vb[d], pf2, o[d], 0, 0, 0);
; #pragma unroll
;     for (int d = 0; d < NDB; ++d) o[d] = __builtin_amdgcn_mfma_f32_32x32x16_bf16(vb[NDB + d], pf3, o[d], 0, 0, 0);
;     lsum += ps;
;     if (__any(ps > 1048576.0f)) {
;         const float pt = ps + __shfl_xor(ps, 32); const float dl = pt > 1048576.0f ? floorf(__log2f(pt)) : 0.f, al = ex2(-dl); mref += dl; lsum *= al;
; #pragma unroll
;         for (int d = 0; d < NDB; ++d)
; #pragma unroll
;             for (int r = 0; r < 16; ++r) o[d][r] *= al;
;     }
.Ldf_509b:
	ds_read_b128 v[172:175], v147 offset:0
	ds_read_b128 v[176:179], v147 offset:4608
	ds_read_b128 v[180:183], v147 offset:9216
	ds_read_b128 v[184:187], v147 offset:13824
	ds_read_b128 v[188:191], v147 offset:32
	ds_read_b128 v[192:195], v147 offset:4640
	ds_read_b128 v[196:199], v147 offset:9248
	ds_read_b128 v[216:219], v147 offset:13856
	s_nop 7
	v_exp_f32_e32 v248, v88
	v_exp_f32_e32 v249, v89
	v_exp_f32_e32 v250, v90
	v_exp_f32_e32 v251, v91
	ds_read_b128 v[88:91], v147 offset:64
	v_exp_f32_e32 v252, v92
	v_exp_f32_e32 v253, v93
	v_exp_f32_e32 v215, v94
	v_exp_f32_e32 v207, v95
	ds_read_b128 v[92:95], v147 offset:4672
	ds_read_b128 v[220:223], v147 offset:9280
	ds_read_b128 v[224:227], v147 offset:13888
	ds_read_b128 v[228:231], v147 offset:96
	ds_read_b128 v[232:235], v147 offset:4704
	v_exp_f32_e32 v161, v80
	v_exp_f32_e32 v168, v81
	v_exp_f32_e32 v169, v82
	v_exp_f32_e32 v171, v83
	v_exp_f32_e32 v244, v84
	v_exp_f32_e32 v245, v85
	v_exp_f32_e32 v246, v86
	v_exp_f32_e32 v247, v87
	ds_read_b128 v[236:239], v147 offset:9312
	ds_read_b128 v[240:243], v147 offset:13920
	v_cvt_pk_bf16_f32 v80, v161, v168
	v_cvt_pk_bf16_f32 v81, v169, v171
	v_cvt_pk_bf16_f32 v82, v244, v245
	v_cvt_pk_bf16_f32 v83, v246, v247
	v_cvt_pk_bf16_f32 v84, v248, v249
	v_cvt_pk_bf16_f32 v85, v250, v251
	v_cvt_pk_bf16_f32 v86, v252, v253
	v_cvt_pk_bf16_f32 v87, v215, v207
	s_waitcnt lgkmcnt(8)
	v_mfma_f32_32x32x16_bf16 v[48:63], v[172:175], v[80:83], v[48:63]
	v_add_f32_e32 v144, 0, v161
	v_add_f32_e32 v144, v168, v144
	v_add_f32_e32 v144, v169, v144
	v_add_f32_e32 v144, v171, v144
	v_add_f32_e32 v144, v244, v144
	v_exp_f32_e32 v161, v68
	v_exp_f32_e32 v168, v69
	v_mfma_f32_32x32x16_bf16 v[32:47], v[176:179], v[80:83], v[32:47]
	v_add_f32_e32 v144, v245, v144
	v_add_f32_e32 v144, v246, v144
	v_add_f32_e32 v144, v247, v144
	v_add_f32_e32 v144, v248, v144
	v_add_f32_e32 v144, v249, v144
	v_exp_f32_e32 v169, v70
	v_exp_f32_e32 v171, v71
	v_mfma_f32_32x32x16_bf16 v[16:31], v[180:183], v[80:83], v[16:31]
	v_add_f32_e32 v144, v250, v144
	v_add_f32_e32 v144, v251, v144
	v_add_f32_e32 v144, v252, v144
	v_add_f32_e32 v144, v253, v144
	v_add_f32_e32 v144, v215, v144
	v_exp_f32_e32 v72, v72
	v_exp_f32_e32 v73, v73
	v_mfma_f32_32x32x16_bf16 v[0:15], v[184:187], v[80:83], v[0:15]
	v_exp_f32_e32 v81, v64
	v_exp_f32_e32 v82, v65
	v_exp_f32_e32 v83, v66
	v_add_f32_e32 v80, v207, v144
	v_exp_f32_e32 v144, v67
	v_add_f32_e32 v80, v81, v80
	v_add_f32_e32 v80, v82, v80
	v_exp_f32_e32 v74, v74
	v_exp_f32_e32 v75, v75
	v_exp_f32_e32 v76, v76
	v_exp_f32_e32 v77, v77
	v_exp_f32_e32 v78, v78
	v_exp_f32_e32 v79, v79
	v_add_f32_e32 v80, v83, v80
	v_add_f32_e32 v80, v144, v80
	v_add_f32_e32 v80, v161, v80
	v_add_f32_e32 v80, v168, v80
	v_cvt_pk_bf16_f32 v64, v81, v82
	v_cvt_pk_bf16_f32 v65, v83, v144
	v_cvt_pk_bf16_f32 v66, v161, v168
	v_cvt_pk_bf16_f32 v67, v169, v171
	v_mfma_f32_32x32x16_bf16 v[48:63], v[188:191], v[84:87], v[48:63]
	v_cvt_pk_bf16_f32 v68, v72, v73
	v_cvt_pk_bf16_f32 v69, v74, v75
	v_cvt_pk_bf16_f32 v70, v76, v77
	v_cvt_pk_bf16_f32 v71, v78, v79
	v_add_f32_e32 v80, v169, v80
	v_add_f32_e32 v80, v171, v80
	v_add_f32_e32 v72, v72, v80
	v_mfma_f32_32x32x16_bf16 v[32:47], v[192:195], v[84:87], v[32:47]
	v_add_f32_e32 v72, v73, v72
	v_add_f32_e32 v72, v74, v72
	v_add_f32_e32 v72, v75, v72
	v_add_f32_e32 v72, v76, v72
	v_add_f32_e32 v72, v77, v72
	v_add_f32_e32 v72, v78, v72
	v_mfma_f32_32x32x16_bf16 v[16:31], v[196:199], v[84:87], v[16:31]
	v_mfma_f32_32x32x16_bf16 v[0:15], v[216:219], v[84:87], v[0:15]
	s_waitcnt lgkmcnt(0)
	s_nop 0
	v_mfma_f32_32x32x16_bf16 v[48:63], v[88:91], v[64:67], v[48:63]
	v_mfma_f32_32x32x16_bf16 v[32:47], v[92:95], v[64:67], v[32:47]
	v_mfma_f32_32x32x16_bf16 v[16:31], v[220:223], v[64:67], v[16:31]
	v_mfma_f32_32x32x16_bf16 v[0:15], v[224:227], v[64:67], v[0:15]
	v_add_f32_e32 v64, v79, v72
	v_add_f32_e32 v162, v162, v64
	v_cmp_lt_f32_e32 vcc, s34, v64
	v_mfma_f32_32x32x16_bf16 v[48:63], v[228:231], v[68:71], v[48:63]
	v_mfma_f32_32x32x16_bf16 v[32:47], v[232:235], v[68:71], v[32:47]
	v_mfma_f32_32x32x16_bf16 v[16:31], v[236:239], v[68:71], v[16:31]
	v_mfma_f32_32x32x16_bf16 v[0:15], v[240:243], v[68:71], v[0:15]
	s_cbranch_vccz .Ldf_503b
	ds_bpermute_b32 v65, v170, v64
	s_waitcnt lgkmcnt(0)
	v_add_f32_e32 v64, v64, v65
	v_log_f32_e32 v65, v64
	v_cmp_lt_f32_e32 vcc, s34, v64
	v_floor_f32_e32 v65, v65
	s_nop 0
	v_cndmask_b32_e32 v65, 0, v65, vcc
	v_exp_f32_e64 v64, -v65
	v_add_f32_e32 v163, v163, v65
	v_mul_f32_e32 v162, v162, v64
	v_pk_mul_f32 v[62:63], v[62:63], v[64:65] op_sel_hi:[1,0]
	v_pk_mul_f32 v[60:61], v[60:61], v[64:65] op_sel_hi:[1,0]
	v_pk_mul_f32 v[58:59], v[58:59], v[64:65] op_sel_hi:[1,0]
	v_pk_mul_f32 v[56:57], v[56:57], v[64:65] op_sel_hi:[1,0]
	v_pk_mul_f32 v[54:55], v[54:55], v[64:65] op_sel_hi:[1,0]
	v_pk_mul_f32 v[52:53], v[52:53], v[64:65] op_sel_hi:[1,0]
	v_pk_mul_f32 v[50:51], v[50:51], v[64:65] op_sel_hi:[1,0]
	v_pk_mul_f32 v[48:49], v[48:49], v[64:65] op_sel_hi:[1,0]
	v_pk_mul_f32 v[46:47], v[46:47], v[64:65] op_sel_hi:[1,0]
	v_pk_mul_f32 v[44:45], v[44:45], v[64:65] op_sel_hi:[1,0]
	v_pk_mul_f32 v[42:43], v[42:43], v[64:65] op_sel_hi:[1,0]
	v_pk_mul_f32 v[40:41], v[40:41], v[64:65] op_sel_hi:[1,0]
	v_pk_mul_f32 v[38:39], v[38:39], v[64:65] op_sel_hi:[1,0]
	v_pk_mul_f32 v[36:37], v[36:37], v[64:65] op_sel_hi:[1,0]
	v_pk_mul_f32 v[34:35], v[34:35], v[64:65] op_sel_hi:[1,0]
	v_pk_mul_f32 v[32:33], v[32:33], v[64:65] op_sel_hi:[1,0]
	v_pk_mul_f32 v[30:31], v[30:31], v[64:65] op_sel_hi:[1,0]
	v_pk_mul_f32 v[28:29], v[28:29], v[64:65] op_sel_hi:[1,0]
	v_pk_mul_f32 v[26:27], v[26:27], v[64:65] op_sel_hi:[1,0]
	v_pk_mul_f32 v[24:25], v[24:25], v[64:65] op_sel_hi:[1,0]
	v_pk_mul_f32 v[22:23], v[22:23], v[64:65] op_sel_hi:[1,0]
	v_pk_mul_f32 v[20:21], v[20:21], v[64:65] op_sel_hi:[1,0]
	v_pk_mul_f32 v[18:19], v[18:19], v[64:65] op_sel_hi:[1,0]
	v_pk_mul_f32 v[16:17], v[16:17], v[64:65] op_sel_hi:[1,0]
	v_pk_mul_f32 v[14:15], v[14:15], v[64:65] op_sel_hi:[1,0]
	v_pk_mul_f32 v[12:13], v[12:13], v[64:65] op_sel_hi:[1,0]
	v_pk_mul_f32 v[10:11], v[10:11], v[64:65] op_sel_hi:[1,0]
	v_pk_mul_f32 v[8:9], v[8:9], v[64:65] op_sel_hi:[1,0]
	v_pk_mul_f32 v[6:7], v[6:7], v[64:65] op_sel_hi:[1,0]
	v_pk_mul_f32 v[4:5], v[4:5], v[64:65] op_sel_hi:[1,0]
	v_pk_mul_f32 v[2:3], v[2:3], v[64:65] op_sel_hi:[1,0]
	v_pk_mul_f32 v[0:1], v[0:1], v[64:65] op_sel_hi:[1,0]
	s_branch .Ldf_503b

; #define ALAS __attribute__((address_space(3)))
; __device__ __forceinline__ int kperm(int i) { return (i & 19) | ((i & 4) << 1) | ((i & 8) >> 1); }
; template <int OFF> __device__ __forceinline__ void ldsr(bf16x8& d, unsigned a) { asm volatile("ds_read_b128 %0, %1 offset:%c2" : "=v"(d) : "v"(a), "i"(OFF) : "memory"); }
; __device__ __forceinline__ void qk_tile(f32x16& s0, f32x16& s1, float ci, const ALAS unsigned char* Kb, const bf16x8 (&qf)[4], int r32, int hi) {
;     const unsigned p0 = (unsigned)(uintptr_t)(Kb + kperm(r32) * ROWB + hi * 16);
;     bf16x8 a[8];
;     ldsr<0>(a[0], p0); ldsr<32 * ROWB>(a[1], p0); ldsr<32>(a[2], p0); ldsr<32 * ROWB + 32>(a[3], p0);
;     ldsr<64>(a[4], p0); ldsr<32 * ROWB + 64>(a[5], p0); ldsr<96>(a[6], p0); ldsr<32 * ROWB + 96>(a[7], p0);
; __device__ __forceinline__ void diff_unit(int b, int hd, int qb, const bf16_t* Q, const bf16_t* K, const bf16_t* VT, bf16_t* O, const float* biasd, float lam, const float* subg, ALAS unsigned char* lds) {
;     ...
;         ALAS unsigned char* buf = lds + (t & 1) * 36864;
; #pragma unroll
;         for (int i = 0; i < 2; ++i) { *(ALAS u32x4*)(buf + kl[i]) = kr[i]; *(ALAS u32x4*)(buf + vl[i]) = vr[i]; }
;         __syncthreads();
;         if (t + 1 < NT) {
; #pragma unroll
;             for (int i = 0; i < 2; ++i) { kr[i] = *(const u32x4*)(kg[i] + (size_t)(t + 1) * 64 * 1024); vr[i] = *(const u32x4*)(vg[i] + (t + 1) * 64); }
;         }
.LBB0_504:
	s_bitcmp1_b32 s14, 0
	s_cselect_b32 s4, 0, 0x9000
	s_add_i32 s18, s4, 0
	s_waitcnt vmcnt(3)
	ds_write_b128 v138, v[112:115] offset:36864
	s_waitcnt vmcnt(1)
	ds_write_b128 v158, v[116:119] offset:55296
	ds_write_b128 v142, v[120:123] offset:36864
	s_cmp_ge_i32 s14, s16
	s_waitcnt vmcnt(0)
	ds_write_b128 v160, v[124:127] offset:55296
	s_waitcnt lgkmcnt(0)
	s_barrier
	ds_read_b128 v[172:175], v146 offset:36864
	ds_read_b128 v[176:179], v146 offset:41472
	ds_read_b128 v[180:183], v146 offset:36896
	ds_read_b128 v[184:187], v146 offset:41504
	ds_read_b128 v[188:191], v146 offset:36928
	ds_read_b128 v[192:195], v146 offset:41536
	ds_read_b128 v[196:199], v146 offset:36960
	ds_read_b128 v[216:219], v146 offset:41568
	s_cbranch_scc1 .LBB0_506
	s_add_i32 s4, s17, 64
	s_lshl_b64 s[36:37], s[4:5], 1
	v_lshl_add_u64 v[64:65], v[156:157], 0, s[36:37]
	v_lshl_add_u64 v[66:67], v[140:141], 0, s[36:37]
	global_load_dwordx4 v[112:115], v[164:165], off
	global_load_dwordx4 v[120:123], v[166:167], off
	global_load_dwordx4 v[116:119], v[66:67], off
	global_load_dwordx4 v[124:127], v[64:65], off

; #define ALAS __attribute__((address_space(3)))
; __device__ __forceinline__ float ex2(float x) { return __builtin_amdgcn_exp2f(x); }
; template <int NDB> __device__ __forceinline__ void wait_v(bf16x8 (&v)[2 * NDB]) { if constexpr (NDB == 4) lds_wait8(v); else lds_wait4(v); }
; template <int NDB>
; __device__ __forceinline__ void softmax_pv(f32x16& s0, f32x16& s1, float& mref, float& lsum, f32x16 (&o)[NDB], const ALAS unsigned char* Vb, int r32, int hi) {
;     const unsigned vp = (unsigned)(uintptr_t)(Vb + r32 * ROWB + hi * 16);
;     bf16x8 va[2 * NDB], vb[2 * NDB];
;     issue_v<NDB, 0>(va, vp);
;     float ps = 0.f;
; #pragma unroll
;     for (int r = 0; r < 16; ++r) { s0[r] = ex2(s0[r]); ps += s0[r]; }
;     bf16x8 pf0, pf1, pf2, pf3;
;     pack16(s0, pf0, pf1);
;     wait_v<NDB>(va);
;     issue_v<NDB, 1>(vb, vp);
;     __builtin_amdgcn_sched_barrier(0);
; #pragma unroll
;     for (int d = 0; d < NDB; ++d) o[d] = __builtin_amdgcn_mfma_f32_32x32x16_bf16(va[d], pf0, o[d], 0, 0, 0);
; #pragma unroll
;     for (int d = 0; d < NDB; ++d) o[d] = __builtin_amdgcn_mfma_f32_32x32x16_bf16(va[NDB + d], pf1, o[d], 0, 0, 0);
; #pragma unroll
;     for (int r = 0; r < 16; ++r) { s1[r] = ex2(s1[r]); ps += s1[r]; }
;     pack16(s1, pf2, pf3);
; #pragma unroll
;     for (int i = 0; i < 2 * NDB; ++i) { __builtin_amdgcn_sched_group_barrier(0x008, 1, 0); __builtin_amdgcn_sched_group_barrier(0x002, (NDB == 4 ? 5 : 10), 0); }
;     __builtin_amdgcn_sched_barrier(0);
;     wait_v<NDB>(vb);
;     __builtin_amdgcn_sched_barrier(0);
; #pragma unroll
;     for (int d = 0; d < NDB; ++d) o[d] = __builtin_amdgcn_mfma_f32_32x32x16_bf16(vb[d], pf2, o[d], 0, 0, 0);
; #pragma unroll
;     for (int d = 0; d < NDB; ++d) o[d] = __builtin_amdgcn_mfma_f32_32x32x16_bf16(vb[NDB + d], pf3, o[d], 0, 0, 0);
;     lsum += ps;
;     if (__any(ps > 1048576.0f)) {
;         const float pt = ps + __shfl_xor(ps, 32); const float dl = pt > 1048576.0f ? floorf(__log2f(pt)) : 0.f, al = ex2(-dl); mref += dl; lsum *= al;
; #pragma unroll
;         for (int d = 0; d < NDB; ++d)
; #pragma unroll
;             for (int r = 0; r < 16; ++r) o[d][r] *= al;
;     }
.LBB0_509:
	ds_read_b128 v[172:175], v147 offset:36864
	ds_read_b128 v[176:179], v147 offset:41472
	ds_read_b128 v[180:183], v147 offset:46080
	ds_read_b128 v[184:187], v147 offset:50688
	ds_read_b128 v[188:191], v147 offset:36896
	ds_read_b128 v[192:195], v147 offset:41504
	ds_read_b128 v[196:199], v147 offset:46112
	ds_read_b128 v[216:219], v147 offset:50720
	s_nop 7
	v_exp_f32_e32 v248, v88
	v_exp_f32_e32 v249, v89
	v_exp_f32_e32 v250, v90
	v_exp_f32_e32 v251, v91
	ds_read_b128 v[88:91], v147 offset:36928
	v_exp_f32_e32 v252, v92
	v_exp_f32_e32 v253, v93
	v_exp_f32_e32 v215, v94
	v_exp_f32_e32 v207, v95
	ds_read_b128 v[92:95], v147 offset:41536
	ds_read_b128 v[220:223], v147 offset:46144
	ds_read_b128 v[224:227], v147 offset:50752
	ds_read_b128 v[228:231], v147 offset:36960
	ds_read_b128 v[232:235], v147 offset:41568
	v_exp_f32_e32 v161, v80
	v_exp_f32_e32 v168, v81
	v_exp_f32_e32 v169, v82
	v_exp_f32_e32 v171, v83
	v_exp_f32_e32 v244, v84
	v_exp_f32_e32 v245, v85
	v_exp_f32_e32 v246, v86
	v_exp_f32_e32 v247, v87
	ds_read_b128 v[236:239], v147 offset:46176
	ds_read_b128 v[240:243], v147 offset:50784
	v_cvt_pk_bf16_f32 v80, v161, v168
	v_cvt_pk_bf16_f32 v81, v169, v171
	v_cvt_pk_bf16_f32 v82, v244, v245
	v_cvt_pk_bf16_f32 v83, v246, v247
	v_cvt_pk_bf16_f32 v84, v248, v249
	v_cvt_pk_bf16_f32 v85, v250, v251
	v_cvt_pk_bf16_f32 v86, v252, v253
	v_cvt_pk_bf16_f32 v87, v215, v207
	s_waitcnt lgkmcnt(8)
	v_mfma_f32_32x32x16_bf16 v[48:63], v[172:175], v[80:83], v[48:63]
	v_add_f32_e32 v144, 0, v161
	v_add_f32_e32 v144, v168, v144
	v_add_f32_e32 v144, v169, v144
	v_add_f32_e32 v144, v171, v144
	v_add_f32_e32 v144, v244, v144
	v_exp_f32_e32 v161, v68
	v_exp_f32_e32 v168, v69
	v_mfma_f32_32x32x16_bf16 v[32:47], v[176:179], v[80:83], v[32:47]
	v_add_f32_e32 v144, v245, v144
	v_add_f32_e32 v144, v246, v144
	v_add_f32_e32 v144, v247, v144
	v_add_f32_e32 v144, v248, v144
	v_add_f32_e32 v144, v249, v144
	v_exp_f32_e32 v169, v70
	v_exp_f32_e32 v171, v71
	v_mfma_f32_32x32x16_bf16 v[16:31], v[180:183], v[80:83], v[16:31]
	v_add_f32_e32 v144, v250, v144
	v_add_f32_e32 v144, v251, v144
	v_add_f32_e32 v144, v252, v144
	v_add_f32_e32 v144, v253, v144
	v_add_f32_e32 v144, v215, v144
	v_exp_f32_e32 v72, v72
	v_exp_f32_e32 v73, v73
	v_mfma_f32_32x32x16_bf16 v[0:15], v[184:187], v[80:83], v[0:15]
	v_exp_f32_e32 v81, v64
	v_exp_f32_e32 v82, v65
	v_exp_f32_e32 v83, v66
	v_add_f32_e32 v80, v207, v144
	v_exp_f32_e32 v144, v67
	v_add_f32_e32 v80, v81, v80
	v_add_f32_e32 v80, v82, v80
	v_exp_f32_e32 v74, v74
	v_exp_f32_e32 v75, v75
	v_exp_f32_e32 v76, v76
	v_exp_f32_e32 v77, v77
	v_exp_f32_e32 v78, v78
	v_exp_f32_e32 v79, v79
	v_add_f32_e32 v80, v83, v80
	v_add_f32_e32 v80, v144, v80
	v_add_f32_e32 v80, v161, v80
	v_add_f32_e32 v80, v168, v80
	v_cvt_pk_bf16_f32 v64, v81, v82
	v_cvt_pk_bf16_f32 v65, v83, v144
	v_cvt_pk_bf16_f32 v66, v161, v168
	v_cvt_pk_bf16_f32 v67, v169, v171
	v_mfma_f32_32x32x16_bf16 v[48:63], v[188:191], v[84:87], v[48:63]
	v_cvt_pk_bf16_f32 v68, v72, v73
	v_cvt_pk_bf16_f32 v69, v74, v75
	v_cvt_pk_bf16_f32 v70, v76, v77
	v_cvt_pk_bf16_f32 v71, v78, v79
	v_add_f32_e32 v80, v169, v80
	v_add_f32_e32 v80, v171, v80
	v_add_f32_e32 v72, v72, v80
	v_mfma_f32_32x32x16_bf16 v[32:47], v[192:195], v[84:87], v[32:47]
	v_add_f32_e32 v72, v73, v72
	v_add_f32_e32 v72, v74, v72
	v_add_f32_e32 v72, v75, v72
	v_add_f32_e32 v72, v76, v72
	v_add_f32_e32 v72, v77, v72
	v_add_f32_e32 v72, v78, v72
	v_mfma_f32_32x32x16_bf16 v[16:31], v[196:199], v[84:87], v[16:31]
	v_mfma_f32_32x32x16_bf16 v[0:15], v[216:219], v[84:87], v[0:15]
	s_waitcnt lgkmcnt(0)
	s_nop 0
	v_mfma_f32_32x32x16_bf16 v[48:63], v[88:91], v[64:67], v[48:63]
	v_mfma_f32_32x32x16_bf16 v[32:47], v[92:95], v[64:67], v[32:47]
	v_mfma_f32_32x32x16_bf16 v[16:31], v[220:223], v[64:67], v[16:31]
	v_mfma_f32_32x32x16_bf16 v[0:15], v[224:227], v[64:67], v[0:15]
	v_add_f32_e32 v64, v79, v72
	v_add_f32_e32 v162, v162, v64
	v_cmp_lt_f32_e32 vcc, s34, v64
	v_mfma_f32_32x32x16_bf16 v[48:63], v[228:231], v[68:71], v[48:63]
	v_mfma_f32_32x32x16_bf16 v[32:47], v[232:235], v[68:71], v[32:47]
	v_mfma_f32_32x32x16_bf16 v[16:31], v[236:239], v[68:71], v[16:31]
	v_mfma_f32_32x32x16_bf16 v[0:15], v[240:243], v[68:71], v[0:15]
	s_cbranch_vccz .LBB0_503
	ds_bpermute_b32 v65, v170, v64
	s_waitcnt lgkmcnt(0)
	v_add_f32_e32 v64, v64, v65
	v_log_f32_e32 v65, v64
	v_cmp_lt_f32_e32 vcc, s34, v64
	v_floor_f32_e32 v65, v65
	s_nop 0
	v_cndmask_b32_e32 v65, 0, v65, vcc
	v_exp_f32_e64 v64, -v65
	v_add_f32_e32 v163, v163, v65
	v_mul_f32_e32 v162, v162, v64
	v_pk_mul_f32 v[62:63], v[62:63], v[64:65] op_sel_hi:[1,0]
	v_pk_mul_f32 v[60:61], v[60:61], v[64:65] op_sel_hi:[1,0]
	v_pk_mul_f32 v[58:59], v[58:59], v[64:65] op_sel_hi:[1,0]
	v_pk_mul_f32 v[56:57], v[56:57], v[64:65] op_sel_hi:[1,0]
	v_pk_mul_f32 v[54:55], v[54:55], v[64:65] op_sel_hi:[1,0]
	v_pk_mul_f32 v[52:53], v[52:53], v[64:65] op_sel_hi:[1,0]
	v_pk_mul_f32 v[50:51], v[50:51], v[64:65] op_sel_hi:[1,0]
	v_pk_mul_f32 v[48:49], v[48:49], v[64:65] op_sel_hi:[1,0]
	v_pk_mul_f32 v[46:47], v[46:47], v[64:65] op_sel_hi:[1,0]
	v_pk_mul_f32 v[44:45], v[44:45], v[64:65] op_sel_hi:[1,0]
	v_pk_mul_f32 v[42:43], v[42:43], v[64:65] op_sel_hi:[1,0]
	v_pk_mul_f32 v[40:41], v[40:41], v[64:65] op_sel_hi:[1,0]
	v_pk_mul_f32 v[38:39], v[38:39], v[64:65] op_sel_hi:[1,0]
	v_pk_mul_f32 v[36:37], v[36:37], v[64:65] op_sel_hi:[1,0]
	v_pk_mul_f32 v[34:35], v[34:35], v[64:65] op_sel_hi:[1,0]
	v_pk_mul_f32 v[32:33], v[32:33], v[64:65] op_sel_hi:[1,0]
	v_pk_mul_f32 v[30:31], v[30:31], v[64:65] op_sel_hi:[1,0]
	v_pk_mul_f32 v[28:29], v[28:29], v[64:65] op_sel_hi:[1,0]
	v_pk_mul_f32 v[26:27], v[26:27], v[64:65] op_sel_hi:[1,0]
	v_pk_mul_f32 v[24:25], v[24:25], v[64:65] op_sel_hi:[1,0]
	v_pk_mul_f32 v[22:23], v[22:23], v[64:65] op_sel_hi:[1,0]
	v_pk_mul_f32 v[20:21], v[20:21], v[64:65] op_sel_hi:[1,0]
	v_pk_mul_f32 v[18:19], v[18:19], v[64:65] op_sel_hi:[1,0]
	v_pk_mul_f32 v[16:17], v[16:17], v[64:65] op_sel_hi:[1,0]
	v_pk_mul_f32 v[14:15], v[14:15], v[64:65] op_sel_hi:[1,0]
	v_pk_mul_f32 v[12:13], v[12:13], v[64:65] op_sel_hi:[1,0]
	v_pk_mul_f32 v[10:11], v[10:11], v[64:65] op_sel_hi:[1,0]
	v_pk_mul_f32 v[8:9], v[8:9], v[64:65] op_sel_hi:[1,0]
	v_pk_mul_f32 v[6:7], v[6:7], v[64:65] op_sel_hi:[1,0]
	v_pk_mul_f32 v[4:5], v[4:5], v[64:65] op_sel_hi:[1,0]
	v_pk_mul_f32 v[2:3], v[2:3], v[64:65] op_sel_hi:[1,0]
	v_pk_mul_f32 v[0:1], v[0:1], v[64:65] op_sel_hi:[1,0]
	s_branch .LBB0_503

; #define SEAM(k) do { if (IN(k) && IN((k) + 1)) { xcd_barrier(bar); } } while (0)
; __device__ __forceinline__ void xcd_barrier(const XcdBarrier& b) {
;     asm volatile("s_waitcnt vmcnt(0)" ::: "memory");
;     __syncthreads();
;     if (threadIdx.x == 0) {
;         unsigned* bar = b.bar;
;         __builtin_amdgcn_s_waitcnt(0);
;         unsigned nloc = b.st[0], nx = b.st[1];
;         if (nloc == 0u) { xcd_barrier_complete(bar, b.x, nloc, nx); b.st[0] = nloc; b.st[1] = nx; }
; __global__ void __launch_bounds__(512, 2) fwd_kernel(Params p) {
;     ...
;         SEAM(pb + 3);
;         if (IN(pb + 4)) { pg8::EpiResid<false> E{nullptr, XA, ss + (size_t)(3 * l + 2) * MTOK * 16, 1.0f}; run_gemm(lds, Ob, Wo, MTOK, 1024, 1024, E); }
.LBB0_546:
	v_mov_b64_e32 v[146:147], 0xb00
	s_mul_i32 s0, s52, 7
	s_add_i32 s4, s0, 5
	s_cmp_lt_i32 s4, s90
	s_cselect_b64 s[0:1], -1, 0
	s_and_b64 s[6:7], s[28:29], s[0:1]
	s_andn2_b64 vcc, exec, s[6:7]
	s_cbranch_vccnz .LBB0_600
	s_waitcnt vmcnt(0)
	s_waitcnt lgkmcnt(0)
	s_barrier
	s_mov_b64 s[6:7], exec
	v_readlane_b32 s8, v254, 3
	v_readlane_b32 s9, v254, 4
	s_and_b64 s[8:9], s[6:7], s[8:9]
	s_mov_b64 exec, s[8:9]
	s_cbranch_execz .LBB0_599
	v_readlane_b32 s8, v255, 24
	s_waitcnt vmcnt(0) expcnt(0) lgkmcnt(0)
	s_nop 0
	v_mov_b32_e32 v0, s8
	ds_read_b32 v2, v0
	v_readlane_b32 s8, v255, 25
	s_waitcnt lgkmcnt(0)
	v_cmp_ne_u32_e32 vcc, 0, v2
	v_mov_b32_e32 v0, s8
	ds_read_b32 v0, v0
	s_cbranch_vccnz .LBB0_563
	s_mov_b32 s14, 1
	s_branch .LBB0_551
